# v31 + even mixer: rotate scan work list; HGRN chain MFMA read-ahead + dword sts writes
# baseline (speedup 1.0000x reference)
.LBB0_640:
	s_or_b64 exec, exec, s[2:3]
	s_mov_b32 s2, s88
	s_waitcnt lgkmcnt(0)
	s_barrier
	s_cmpk_gt_i32 s2, 0x39f
	s_cbranch_scc1 .LBB0_676
	v_readlane_b32 s6, v255, 4
	v_readlane_b32 s0, v254, 60
	v_readlane_b32 s7, v255, 5
	v_readlane_b32 s1, v254, 61
	s_sub_i32 s25, s2, 32
	s_lshl_b64 s[10:11], s[6:7], 16
	s_load_dwordx2 s[28:29], s[0:1], 0x128
	s_add_u32 s26, s50, 0x14712000
	s_addc_u32 s27, s51, 0
	s_add_u32 s30, s50, 0x25f91400
	s_addc_u32 s31, s51, 0
	s_lshl_b64 s[4:5], s[6:7], 14
	s_waitcnt lgkmcnt(0)
	s_add_u32 s44, s28, s4
	s_addc_u32 s45, s29, s5
	s_lshl_b64 s[34:35], s[6:7], 9
	s_load_dwordx4 s[12:15], s[0:1], 0x10
	s_load_dwordx4 s[16:19], s[0:1], 0x70
	s_cmp_eq_u32 s6, 1
	s_cselect_b64 s[36:37], -1, 0
	s_add_u32 s38, s50, 0x2c598800
	s_addc_u32 s39, s51, 0
	s_lshl_b32 s3, s2, 6
	s_lshl_b32 s2, s2, 4
	s_add_i32 s52, s3, 0xfffff800
	s_add_i32 s53, s2, 0xfffffe00
	v_readlane_b32 s98, v253, 8
	s_lshr_b32 s99, s98, 1
	s_add_i32 s25, s25, s99
	s_cmp_ge_u32 s25, s98
	s_cselect_b32 s99, s98, 0
	s_sub_i32 s25, s25, s99
	s_lshl_b32 s52, s25, 6
	s_lshl_b32 s53, s25, 4
	s_add_i32 s54, s89, 0x8000
	s_add_i32 s55, s89, 0x6000
	s_branch .LBB0_644

.LBB0_679:
	v_mul_f32_e32 v0, 0x3fb8aa3b, v0
	v_exp_f32_e32 v14, v0
	v_mul_f32_e32 v0, 0x3fb8aa3b, v2
	v_exp_f32_e32 v12, v0
	v_mul_f32_e32 v0, 0x3fb8aa3b, v4
	v_exp_f32_e32 v10, v0
	v_mul_f32_e32 v0, 0x3fb8aa3b, v6
	v_exp_f32_e32 v8, v0
	v_mul_f32_e32 v0, 0x3fb8aa3b, v16
	v_exp_f32_e32 v6, v0
	v_mul_f32_e32 v0, 0x3fb8aa3b, v78
	v_exp_f32_e32 v4, v0
	v_mul_f32_e32 v0, 0x3fb8aa3b, v79
	v_lshl_add_u64 v[78:79], s[50:51], 0, v[140:141]
	s_mov_b64 s[6:7], 0x14711c00
	v_exp_f32_e32 v2, v0
	v_mul_f32_e32 v0, 0x3fb8aa3b, v80
	v_lshl_add_u64 v[80:81], v[78:79], 0, s[6:7]
	s_mov_b32 s6, 0x14711000
	v_add_co_u32_e32 v78, vcc, s6, v78
	v_pk_mul_f32 v[48:49], v[14:15], v[48:49] op_sel_hi:[0,1]
	s_nop 0
	v_addc_co_u32_e32 v79, vcc, 0, v79, vcc
	global_load_dwordx4 v[82:85], v[78:79], off offset:3072
	s_nop 0
	global_load_dwordx4 v[78:81], v[80:81], off offset:16
	s_waitcnt lgkmcnt(0)
	s_barrier
	v_mul_f32_e64 v46, v14, v46
	v_mul_f32_e64 v47, v14, v47
	v_pk_mul_f32 v[76:77], v[12:13], v[76:77] op_sel_hi:[0,1]
	v_pk_mul_f32 v[74:75], v[12:13], v[74:75] op_sel_hi:[0,1]
	v_mul_f32_e64 v68, v10, v68
	v_mul_f32_e64 v69, v10, v69
	v_pk_mul_f32 v[66:67], v[10:11], v[66:67] op_sel_hi:[0,1]
	v_pk_mul_f32 v[60:61], v[8:9], v[60:61] op_sel_hi:[0,1]
	v_mul_f32_e64 v58, v8, v58
	v_mul_f32_e64 v59, v8, v59
	v_pk_mul_f32 v[56:57], v[6:7], v[56:57] op_sel_hi:[0,1]
	v_pk_mul_f32 v[54:55], v[6:7], v[54:55] op_sel_hi:[0,1]
	v_pk_mul_f32 v[52:53], v[4:5], v[52:53] op_sel_hi:[0,1]
	v_pk_mul_f32 v[50:51], v[4:5], v[50:51] op_sel_hi:[0,1]
	v_pk_mul_f32 v[72:73], v[2:3], v[72:73] op_sel_hi:[0,1]
	v_pk_mul_f32 v[70:71], v[2:3], v[70:71] op_sel_hi:[0,1]
	v_exp_f32_e32 v0, v0
	s_nop 0
	v_add_u32_e32 v2, 0x8c00, v202
	v_pk_mul_f32 v[64:65], v[0:1], v[64:65] op_sel_hi:[0,1]
	v_pk_mul_f32 v[62:63], v[0:1], v[62:63] op_sel_hi:[0,1]
	v_add_u32_e32 v0, 0x8800, v202
	v_and_b32_e32 v4, 64, v177
	v_add_u32_e32 v4, 64, v4
	s_mov_b32 s0, 0x25f91000
	s_add_i32 s5, s5, -1
	s_mov_b64 s[6:7], 0x20000
	v_lshl_add_u64 v[132:133], v[132:133], 0, s[8:9]
	v_lshl_add_u64 v[134:135], v[134:135], 0, s[8:9]
	v_lshl_add_u64 v[136:137], v[136:137], 0, s[8:9]
	v_lshl_add_u64 v[140:141], v[140:141], 0, s[86:87]
	s_cmp_lg_u32 s5, 0
	s_nop 1
	ds_read_b128 v[218:221], v160
	ds_read_b128 v[222:225], v124
	ds_read_b128 v[226:229], v125
	ds_read_b128 v[240:243], v193
	ds_read_b128 v[244:247], v126
	ds_read_b128 v[248:251], v160 offset:64
	ds_read_b128 v[144:147], v124 offset:64
	s_waitcnt lgkmcnt(5)
	v_mfma_f32_16x16x32_bf16 v[86:89], v[218:221], v[222:225], 0
	ds_read_b128 v[180:183], v125 offset:64
	s_waitcnt lgkmcnt(5)
	v_mfma_f32_16x16x32_bf16 v[90:93], v[218:221], v[226:229], 0
	ds_read_b128 v[222:225], v193 offset:64
	s_waitcnt lgkmcnt(5)
	v_mfma_f32_16x16x32_bf16 v[94:97], v[218:221], v[240:243], 0
	ds_read_b128 v[226:229], v126 offset:64
	s_waitcnt lgkmcnt(5)
	v_mfma_f32_16x16x32_bf16 v[98:101], v[218:221], v[244:247], 0
	ds_read_b128 v[240:243], v160 offset:128
	ds_read_b128 v[218:221], v124 offset:128
	s_waitcnt lgkmcnt(5)
	v_mfma_f32_16x16x32_bf16 v[86:89], v[248:251], v[144:147], v[86:89]
	ds_read_b128 v[244:247], v125 offset:128
	s_waitcnt lgkmcnt(5)
	v_mfma_f32_16x16x32_bf16 v[90:93], v[248:251], v[180:183], v[90:93]
	ds_read_b128 v[144:147], v193 offset:128
	s_waitcnt lgkmcnt(5)
	v_mfma_f32_16x16x32_bf16 v[94:97], v[248:251], v[222:225], v[94:97]
	ds_read_b128 v[180:183], v126 offset:128
	s_waitcnt lgkmcnt(5)
	v_mfma_f32_16x16x32_bf16 v[98:101], v[248:251], v[226:229], v[98:101]
	ds_read_b128 v[222:225], v160 offset:192
	ds_read_b128 v[248:251], v124 offset:192
	s_waitcnt lgkmcnt(5)
	v_mfma_f32_16x16x32_bf16 v[86:89], v[240:243], v[218:221], v[86:89]
	ds_read_b128 v[226:229], v125 offset:192
	s_waitcnt lgkmcnt(5)
	v_mfma_f32_16x16x32_bf16 v[90:93], v[240:243], v[244:247], v[90:93]
	ds_read_b128 v[218:221], v193 offset:192
	s_waitcnt lgkmcnt(5)
	v_mfma_f32_16x16x32_bf16 v[94:97], v[240:243], v[144:147], v[94:97]
	ds_read_b128 v[244:247], v126 offset:192
	s_waitcnt lgkmcnt(5)
	v_mfma_f32_16x16x32_bf16 v[98:101], v[240:243], v[180:183], v[98:101]
	ds_read_b128 v[144:147], v161
	ds_read_b128 v[240:243], v128 offset:53248
	s_waitcnt lgkmcnt(5)
	v_mfma_f32_16x16x32_bf16 v[86:89], v[222:225], v[248:251], v[86:89]
	ds_read_b128 v[180:183], v127 offset:53248
	s_waitcnt lgkmcnt(5)
	v_mfma_f32_16x16x32_bf16 v[90:93], v[222:225], v[226:229], v[90:93]
	ds_read_b128 v[248:251], v129 offset:53248
	s_waitcnt lgkmcnt(5)
	v_mfma_f32_16x16x32_bf16 v[94:97], v[222:225], v[218:221], v[94:97]
	ds_read_b128 v[226:229], v130 offset:53248
	s_waitcnt lgkmcnt(5)
	v_mfma_f32_16x16x32_bf16 v[98:101], v[222:225], v[244:247], v[98:101]
	ds_read_b128 v[218:221], v161 offset:64
	ds_read_b128 v[222:225], v128 offset:53312
	s_waitcnt lgkmcnt(5)
	v_mfma_f32_16x16x32_bf16 v[86:89], v[144:147], v[240:243], v[86:89]
	ds_read_b128 v[244:247], v127 offset:53312
	s_waitcnt lgkmcnt(5)
	v_mfma_f32_16x16x32_bf16 v[90:93], v[144:147], v[180:183], v[90:93]
	ds_read_b128 v[240:243], v129 offset:53312
	s_waitcnt lgkmcnt(5)
	v_mfma_f32_16x16x32_bf16 v[94:97], v[144:147], v[248:251], v[94:97]
	ds_read_b128 v[180:183], v130 offset:53312
	s_waitcnt lgkmcnt(5)
	v_mfma_f32_16x16x32_bf16 v[98:101], v[144:147], v[226:229], v[98:101]
	ds_read_b128 v[248:251], v120 offset:53248
	ds_read_b128 v[144:147], v120 offset:53312
	s_waitcnt lgkmcnt(5)
	v_mfma_f32_16x16x32_bf16 v[86:89], v[218:221], v[222:225], v[86:89]
	ds_read_b128 v[226:229], v131 offset:34816
	s_waitcnt lgkmcnt(5)
	v_mfma_f32_16x16x32_bf16 v[90:93], v[218:221], v[244:247], v[90:93]
	ds_read_b128 v[222:225], v195 offset:34816
	s_waitcnt lgkmcnt(5)
	v_mfma_f32_16x16x32_bf16 v[94:97], v[218:221], v[240:243], v[94:97]
	ds_read_b128 v[244:247], v196 offset:34816
	s_waitcnt lgkmcnt(5)
	v_mfma_f32_16x16x32_bf16 v[98:101], v[218:221], v[180:183], v[98:101]
	ds_read_b128 v[240:243], v197 offset:34816
	ds_read_b128 v[218:221], v198 offset:34816
	ds_read_b128 v[180:183], v199 offset:34816
	s_waitcnt lgkmcnt(5)
	v_mfma_f32_16x16x32_bf16 v[46:49], v[248:251], v[226:229], v[46:49]
	ds_read_b128 v[226:229], v200 offset:34816
	s_waitcnt lgkmcnt(5)
	v_mfma_f32_16x16x32_bf16 v[74:77], v[248:251], v[222:225], v[74:77]
	ds_read_b128 v[222:225], v201 offset:34816
	s_waitcnt lgkmcnt(5)
	v_mfma_f32_16x16x32_bf16 v[66:69], v[248:251], v[244:247], v[66:69]
	ds_read_b128 v[244:247], v131 offset:34880
	s_waitcnt lgkmcnt(5)
	v_mfma_f32_16x16x32_bf16 v[58:61], v[248:251], v[240:243], v[58:61]
	ds_read_b128 v[240:243], v195 offset:34880
	s_waitcnt lgkmcnt(5)
	v_mfma_f32_16x16x32_bf16 v[54:57], v[248:251], v[218:221], v[54:57]
	ds_read_b128 v[218:221], v196 offset:34880
	s_waitcnt lgkmcnt(5)
	v_mfma_f32_16x16x32_bf16 v[50:53], v[248:251], v[180:183], v[50:53]
	ds_read_b128 v[180:183], v197 offset:34880
	s_waitcnt lgkmcnt(5)
	v_mfma_f32_16x16x32_bf16 v[70:73], v[248:251], v[226:229], v[70:73]
	ds_read_b128 v[226:229], v198 offset:34880
	s_waitcnt lgkmcnt(5)
	v_mfma_f32_16x16x32_bf16 v[62:65], v[248:251], v[222:225], v[62:65]
	ds_read_b128 v[248:251], v199 offset:34880
	s_waitcnt lgkmcnt(5)
	v_mfma_f32_16x16x32_bf16 v[46:49], v[144:147], v[244:247], v[46:49]
	ds_read_b128 v[222:225], v200 offset:34880
	s_waitcnt lgkmcnt(5)
	v_mfma_f32_16x16x32_bf16 v[74:77], v[144:147], v[240:243], v[74:77]
	ds_read_b128 v[244:247], v201 offset:34880
	s_waitcnt lgkmcnt(5)
	v_mfma_f32_16x16x32_bf16 v[66:69], v[144:147], v[218:221], v[66:69]
	s_waitcnt lgkmcnt(4)
	v_mfma_f32_16x16x32_bf16 v[58:61], v[144:147], v[180:183], v[58:61]
	s_waitcnt lgkmcnt(3)
	v_mfma_f32_16x16x32_bf16 v[54:57], v[144:147], v[226:229], v[54:57]
	s_waitcnt lgkmcnt(2)
	v_mfma_f32_16x16x32_bf16 v[50:53], v[144:147], v[248:251], v[50:53]
	s_waitcnt lgkmcnt(1)
	v_mfma_f32_16x16x32_bf16 v[70:73], v[144:147], v[222:225], v[70:73]
	s_waitcnt lgkmcnt(0)
	v_mfma_f32_16x16x32_bf16 v[62:65], v[144:147], v[244:247], v[62:65]
	s_waitcnt lgkmcnt(0)
	s_barrier
	ds_write2_b32 v0, v86, v90 offset1:16
	ds_write2_b32 v2, v88, v92 offset0:8 offset1:24
	ds_write2_b32 v0, v94, v87 offset0:32 offset1:132
	ds_write2_b32 v0, v91, v95 offset0:148 offset1:164
	ds_write2_b32 v2, v96, v89 offset0:40 offset1:140
	ds_write2_b32 v2, v93, v97 offset0:156 offset1:172
	v_add_u32_e32 v0, 0x8800, v203
	ds_write2_b32 v0, v98, v99 offset1:132
	v_add_u32_e32 v0, 0x8c00, v203
	ds_write2_b32 v0, v100, v101 offset0:8 offset1:140
	s_waitcnt lgkmcnt(0)
	s_barrier
	ds_read_b128 v[98:101], v207 offset:34816
	ds_read_b128 v[90:93], v207 offset:34832
	ds_read_b128 v[94:97], v207 offset:34848
	ds_read_b128 v[86:89], v207 offset:34864
	s_waitcnt lgkmcnt(3)
	v_mov_b32_e32 v220, v99
	s_waitcnt lgkmcnt(2)
	v_mov_b32_e32 v221, v91
	v_mov_b32_e32 v218, v98
	v_mov_b32_e32 v219, v90
	v_pk_mul_f32 v[220:221], v[220:221], v[220:221]
	s_waitcnt lgkmcnt(1)
	v_mov_b32_e32 v222, v95
	v_pk_fma_f32 v[218:219], v[218:219], v[218:219], v[220:221]
	v_mov_b32_e32 v220, v100
	v_mov_b32_e32 v221, v92
	v_pk_fma_f32 v[218:219], v[220:221], v[220:221], v[218:219]
	v_mov_b32_e32 v220, v101
	v_mov_b32_e32 v221, v93
	s_waitcnt lgkmcnt(0)
	v_mov_b32_e32 v223, v87
	v_pk_fma_f32 v[218:219], v[220:221], v[220:221], v[218:219]
	v_mov_b32_e32 v220, v94
	v_mov_b32_e32 v221, v86
	v_pk_mul_f32 v[222:223], v[222:223], v[222:223]
	v_xor_b32_e32 v2, 1, v177
	v_pk_fma_f32 v[220:221], v[220:221], v[220:221], v[222:223]
	v_mov_b32_e32 v222, v96
	v_mov_b32_e32 v223, v88
	v_pk_fma_f32 v[220:221], v[222:223], v[222:223], v[220:221]
	v_mov_b32_e32 v222, v97
	v_mov_b32_e32 v223, v89
	v_pk_fma_f32 v[220:221], v[222:223], v[222:223], v[220:221]
	v_add_f32_e32 v0, v218, v219
	v_cmp_lt_i32_e32 vcc, v2, v4
	v_add_f32_e32 v0, v0, v220
	v_add_f32_e32 v0, v0, v221
	v_cndmask_b32_e32 v2, v177, v2, vcc
	v_lshlrev_b32_e32 v2, 2, v2
	ds_bpermute_b32 v2, v2, v0
	s_waitcnt vmcnt(1)
	v_lshlrev_b32_e32 v218, 16, v82
	s_waitcnt lgkmcnt(0)
	v_add_f32_e32 v0, v0, v2
	v_xor_b32_e32 v2, 2, v177
	v_cmp_lt_i32_e32 vcc, v2, v4
	s_nop 1
	v_cndmask_b32_e32 v2, v177, v2, vcc
	v_lshlrev_b32_e32 v2, 2, v2
	ds_bpermute_b32 v2, v2, v0
	s_waitcnt lgkmcnt(0)
	v_add_f32_e32 v0, v0, v2
	v_xor_b32_e32 v2, 4, v177
	v_cmp_lt_i32_e32 vcc, v2, v4
	s_nop 1
	v_cndmask_b32_e32 v2, v177, v2, vcc
	v_lshlrev_b32_e32 v2, 2, v2
	ds_bpermute_b32 v2, v2, v0
	s_waitcnt lgkmcnt(0)
	v_add_f32_e32 v0, v0, v2
	v_fmamk_f32 v0, v0, 0x3c000000, v143
	v_cmp_gt_f32_e32 vcc, s90, v0
	v_mul_f32_e32 v2, 0x4b800000, v0
	s_nop 0
	v_cndmask_b32_e32 v0, v0, v2, vcc
	v_rsq_f32_e32 v0, v0
	s_nop 0
	v_mul_f32_e32 v2, 0x45800000, v0
	v_cndmask_b32_e32 v0, v0, v2, vcc
	v_mul_f32_e32 v2, 0xbfb8aa3b, v218
	v_exp_f32_e32 v2, v2
	v_mul_f32_e32 v219, v98, v0
	v_and_b32_e32 v98, 0xffff0000, v82
	v_mul_f32_e32 v99, v99, v0
	v_add_f32_e32 v2, 1.0, v2
	v_rcp_f32_e32 v102, v2
	v_mul_f32_e32 v2, 0xbfb8aa3b, v98
	v_exp_f32_e32 v2, v2
	v_mul_f32_e32 v95, v95, v0
	v_pk_mul_f32 v[218:219], v[102:103], v[218:219]
	v_mul_f32_e32 v91, v91, v0
	v_add_f32_e32 v2, 1.0, v2
	v_rcp_f32_e32 v2, v2
	v_mul_f32_e32 v4, v218, v219
	v_mul_f32_e32 v87, v87, v0
	v_pk_mul_f32 v[98:99], v[2:3], v[98:99]
	s_nop 0
	v_mul_f32_e32 v2, v98, v99
	v_mul_f32_e32 v99, v94, v0
	s_waitcnt vmcnt(0)
	v_lshlrev_b32_e32 v98, 16, v78
	v_and_b32_e32 v94, 0xffff0000, v78
	v_cvt_pk_bf16_f32 v82, v4, v2
	v_mul_f32_e32 v2, 0xbfb8aa3b, v98
	v_mul_f32_e32 v4, 0xbfb8aa3b, v94
	v_exp_f32_e32 v2, v2
	v_exp_f32_e32 v4, v4
	v_add_f32_e32 v2, 1.0, v2
	v_add_f32_e32 v4, 1.0, v4
	v_rcp_f32_e32 v110, v2
	v_rcp_f32_e32 v10, v4
	v_pk_mul_f32 v[98:99], v[110:111], v[98:99]
	v_pk_mul_f32 v[94:95], v[10:11], v[94:95]
	v_mul_f32_e32 v2, v98, v99
	v_mul_f32_e32 v4, v94, v95
	v_lshlrev_b32_e32 v94, 16, v83
	v_cvt_pk_bf16_f32 v78, v2, v4
	v_mul_f32_e32 v2, 0xbfb8aa3b, v94
	v_exp_f32_e32 v2, v2
	v_mul_f32_e32 v95, v100, v0
	v_add_f32_e32 v2, 1.0, v2
	v_rcp_f32_e32 v104, v2
	s_nop 0
	v_pk_mul_f32 v[94:95], v[104:105], v[94:95]
	s_nop 0
	v_mul_f32_e32 v2, v94, v95
	v_and_b32_e32 v94, 0xffff0000, v83
	v_mul_f32_e32 v4, 0xbfb8aa3b, v94
	v_exp_f32_e32 v4, v4
	v_mul_f32_e32 v95, v101, v0
	v_add_f32_e32 v4, 1.0, v4
	v_rcp_f32_e32 v4, v4
	s_nop 0
	v_pk_mul_f32 v[94:95], v[4:5], v[94:95]
	s_nop 0
	v_mul_f32_e32 v4, v94, v95
	v_lshlrev_b32_e32 v94, 16, v79
	v_cvt_pk_bf16_f32 v83, v2, v4
	v_mul_f32_e32 v2, 0xbfb8aa3b, v94
	v_exp_f32_e32 v2, v2
	v_mul_f32_e32 v95, v96, v0
	v_add_f32_e32 v2, 1.0, v2
	v_rcp_f32_e32 v112, v2
	s_nop 0
	v_pk_mul_f32 v[94:95], v[112:113], v[94:95]
	s_nop 0
	v_mul_f32_e32 v2, v94, v95
	v_and_b32_e32 v94, 0xffff0000, v79
	v_mul_f32_e32 v4, 0xbfb8aa3b, v94
	v_exp_f32_e32 v4, v4
	v_mul_f32_e32 v95, v97, v0
	v_add_f32_e32 v4, 1.0, v4
	v_rcp_f32_e32 v12, v4
	s_nop 0
	v_pk_mul_f32 v[94:95], v[12:13], v[94:95]
	s_nop 0
	v_mul_f32_e32 v4, v94, v95
	v_mul_f32_e32 v95, v90, v0
	v_lshlrev_b32_e32 v94, 16, v84
	v_and_b32_e32 v90, 0xffff0000, v84
	v_cvt_pk_bf16_f32 v79, v2, v4
	v_mul_f32_e32 v2, 0xbfb8aa3b, v94
	v_mul_f32_e32 v4, 0xbfb8aa3b, v90
	v_exp_f32_e32 v2, v2
	v_exp_f32_e32 v4, v4
	v_add_f32_e32 v2, 1.0, v2
	v_add_f32_e32 v4, 1.0, v4
	v_rcp_f32_e32 v106, v2
	v_rcp_f32_e32 v6, v4
	v_pk_mul_f32 v[94:95], v[106:107], v[94:95]
	v_pk_mul_f32 v[90:91], v[6:7], v[90:91]
	v_mul_f32_e32 v2, v94, v95
	v_mul_f32_e32 v4, v90, v91
	v_mul_f32_e32 v91, v86, v0
	v_lshlrev_b32_e32 v90, 16, v80
	v_and_b32_e32 v86, 0xffff0000, v80
	v_cvt_pk_bf16_f32 v84, v2, v4
	v_mul_f32_e32 v2, 0xbfb8aa3b, v90
	v_mul_f32_e32 v4, 0xbfb8aa3b, v86
	v_exp_f32_e32 v2, v2
	v_exp_f32_e32 v4, v4
	v_mov_b32_e32 v6, v211
	v_add_f32_e32 v2, 1.0, v2
	v_add_f32_e32 v4, 1.0, v4
	v_rcp_f32_e32 v114, v2
	v_rcp_f32_e32 v14, v4
	v_pk_mul_f32 v[90:91], v[114:115], v[90:91]
	v_pk_mul_f32 v[86:87], v[14:15], v[86:87]
	v_mul_f32_e32 v2, v90, v91
	v_mul_f32_e32 v4, v86, v87
	v_lshlrev_b32_e32 v86, 16, v85
	v_cvt_pk_bf16_f32 v80, v2, v4
	v_mul_f32_e32 v2, 0xbfb8aa3b, v86
	v_exp_f32_e32 v2, v2
	v_mul_f32_e32 v87, v92, v0
	v_add_f32_e32 v2, 1.0, v2
	v_rcp_f32_e32 v108, v2
	s_nop 0
	v_pk_mul_f32 v[86:87], v[108:109], v[86:87]
	s_nop 0
	v_mul_f32_e32 v2, v86, v87
	v_and_b32_e32 v86, 0xffff0000, v85
	v_mul_f32_e32 v4, 0xbfb8aa3b, v86
	v_exp_f32_e32 v4, v4
	v_mul_f32_e32 v87, v93, v0
	v_add_f32_e32 v4, 1.0, v4
	v_rcp_f32_e32 v8, v4
	s_nop 0
	v_pk_mul_f32 v[86:87], v[8:9], v[86:87]
	s_nop 0
	v_mul_f32_e32 v4, v86, v87
	v_lshlrev_b32_e32 v86, 16, v81
	v_cvt_pk_bf16_f32 v85, v2, v4
	v_mul_f32_e32 v2, 0xbfb8aa3b, v86
	v_exp_f32_e32 v2, v2
	v_mul_f32_e32 v87, v88, v0
	v_mov_b32_e32 v4, v210
	v_add_f32_e32 v2, 1.0, v2
	v_rcp_f32_e32 v116, v2
	s_nop 0
	v_pk_mul_f32 v[86:87], v[116:117], v[86:87]
	s_nop 0
	v_mul_f32_e32 v2, v86, v87
	v_and_b32_e32 v86, 0xffff0000, v81
	v_mul_f32_e32 v87, v89, v0
	v_mul_f32_e32 v0, 0xbfb8aa3b, v86
	v_exp_f32_e32 v0, v0
	s_nop 0
	v_add_f32_e32 v0, 1.0, v0
	v_rcp_f32_e32 v16, v0
	s_nop 0
	v_pk_mul_f32 v[86:87], v[16:17], v[86:87]
	s_nop 0
	v_mul_f32_e32 v0, v86, v87
	v_lshl_add_u64 v[86:87], s[50:51], 0, v[138:139]
	v_add_co_u32_e32 v86, vcc, s0, v86
	v_cvt_pk_bf16_f32 v81, v2, v0
	v_lshl_add_u64 v[138:139], v[138:139], 0, s[6:7]
	s_nop 0
	v_addc_co_u32_e32 v87, vcc, 0, v87, vcc
	global_store_dwordx4 v[86:87], v[82:85], off
	global_store_dwordx4 v[86:87], v[78:81], off offset:16
	v_mov_b32_e32 v0, v208
	v_mov_b32_e32 v2, v209
	v_mov_b32_e32 v16, v212
	v_mov_b32_e32 v78, v213
	v_mov_b32_e32 v79, v214
	v_mov_b32_e32 v80, v215
	s_cbranch_scc0 .LBB0_682
